# v52 plus QK MFMA issued before the V-fragment LDS reads in every gap of the QK phase (MFMA-only segment heads)
# baseline (speedup 1.0000x reference)
.LBB0_618:
	v_mfma_f32_32x32x16_bf16 v[114:129], v[190:193], v[150:153], v[34:49]
	ds_read_b64_tr_b16 v[52:53], v199 offset:24576
	ds_read_b64_tr_b16 v[54:55], v199 offset:25088
	v_add_f32_e32 v50, v82, v50
	v_add_f32_e32 v194, v83, v194
	v_add_f32_e32 v195, v84, v195
	v_add_f32_e32 v196, v85, v196
	v_add_f32_e32 v50, v86, v50
	v_add_f32_e32 v194, v87, v194
	v_cvt_pk_bf16_f32 v158, v82, v83
	v_cvt_pk_bf16_f32 v159, v84, v85
	v_mfma_f32_32x32x16_bf16 v[98:113], v[186:189], v[150:153], v[34:49]
	ds_read_b64_tr_b16 v[60:61], v199 offset:28672
	ds_read_b64_tr_b16 v[62:63], v199 offset:29184
	v_add_f32_e32 v195, v88, v195
	v_add_f32_e32 v196, v89, v196
	v_add_f32_e32 v50, v90, v50
	v_add_f32_e32 v194, v91, v194
	v_cvt_pk_bf16_f32 v160, v86, v87
	v_cvt_pk_bf16_f32 v161, v88, v89
	v_mfma_f32_32x32x16_bf16 v[114:129], v[182:185], v[138:141], v[114:129]
	ds_read_b64_tr_b16 v[82:83], v199 offset:25600
	ds_read_b64_tr_b16 v[84:85], v199 offset:26112
	v_add_f32_e32 v195, v92, v195
	v_add_f32_e32 v196, v93, v196
	v_add_f32_e32 v50, v94, v50
	v_add_f32_e32 v194, v95, v194
	v_cvt_pk_bf16_f32 v154, v90, v91
	v_cvt_pk_bf16_f32 v155, v92, v93
	v_mfma_f32_32x32x16_bf16 v[98:113], v[178:181], v[138:141], v[98:113]
	ds_read_b64_tr_b16 v[86:87], v199 offset:29696
	ds_read_b64_tr_b16 v[88:89], v199 offset:30208
	v_add_f32_e32 v195, v96, v195
	v_add_f32_e32 v196, v97, v196
	v_add_f32_e32 v50, v66, v50
	v_add_f32_e32 v194, v67, v194
	v_cvt_pk_bf16_f32 v156, v94, v95
	v_cvt_pk_bf16_f32 v157, v96, v97
	v_mfma_f32_32x32x16_bf16 v[114:129], v[174:177], v[134:137], v[114:129]
	ds_read_b64_tr_b16 v[90:91], v199 offset:26624
	ds_read_b64_tr_b16 v[92:93], v199 offset:27136
	v_add_f32_e32 v195, v68, v195
	v_add_f32_e32 v196, v69, v196
	v_add_f32_e32 v50, v70, v50
	v_add_f32_e32 v194, v71, v194
	v_cvt_pk_bf16_f32 v146, v66, v67
	v_cvt_pk_bf16_f32 v147, v68, v69
	v_mfma_f32_32x32x16_bf16 v[98:113], v[170:173], v[134:137], v[98:113]
	ds_read_b64_tr_b16 v[64:65], v199 offset:30720
	ds_read_b64_tr_b16 v[66:67], v199 offset:31232
	v_add_f32_e32 v195, v72, v195
	v_add_f32_e32 v196, v73, v196
	v_add_f32_e32 v50, v74, v50
	v_add_f32_e32 v194, v75, v194
	v_cvt_pk_bf16_f32 v148, v70, v71
	v_cvt_pk_bf16_f32 v149, v72, v73
	v_mfma_f32_32x32x16_bf16 v[114:129], v[166:169], v[130:133], v[114:129]
	ds_read_b64_tr_b16 v[68:69], v199 offset:27648
	ds_read_b64_tr_b16 v[70:71], v199 offset:28160
	v_add_f32_e32 v195, v76, v195
	v_add_f32_e32 v196, v77, v196
	v_add_f32_e32 v50, v78, v50
	v_add_f32_e32 v194, v79, v194
	v_cvt_pk_bf16_f32 v142, v74, v75
	v_cvt_pk_bf16_f32 v143, v76, v77
	v_mfma_f32_32x32x16_bf16 v[98:113], v[162:165], v[130:133], v[98:113]
	ds_read_b64_tr_b16 v[72:73], v199 offset:31744
	ds_read_b64_tr_b16 v[74:75], v199 offset:32256
	v_add_f32_e32 v195, v80, v195
	v_add_f32_e32 v196, v81, v196
	v_cvt_pk_bf16_f32 v144, v78, v79
	v_cvt_pk_bf16_f32 v145, v80, v81
	s_add_i32 m0, s31, s70
	s_add_i32 s6, s76, s71
	global_load_lds_dwordx4 v197, s[98:99]
	s_mov_b32 m0, s6
	s_nop 0
	global_load_lds_dwordx4 v205, s[98:99]
	s_add_u32 s98, s98, 0x2000
	s_addc_u32 s99, s99, 0
	s_waitcnt lgkmcnt(14)
	v_mfma_f32_32x32x16_bf16 v[2:17], v[158:161], v[52:55], v[2:17]
	v_exp_f32_e32 v114, v114
	v_exp_f32_e32 v115, v115
	v_exp_f32_e32 v116, v116
	v_exp_f32_e32 v117, v117
	s_waitcnt lgkmcnt(12)
	v_mfma_f32_32x32x16_bf16 v[18:33], v[158:161], v[60:63], v[18:33]
	v_exp_f32_e32 v118, v118
	v_exp_f32_e32 v119, v119
	v_exp_f32_e32 v120, v120
	v_exp_f32_e32 v121, v121
	ds_read_b128 v[60:63], v204
	ds_read_b128 v[162:165], v204 offset:512
	s_waitcnt lgkmcnt(12)
	v_mfma_f32_32x32x16_bf16 v[2:17], v[154:157], v[82:85], v[2:17]
	v_exp_f32_e32 v122, v122
	v_exp_f32_e32 v123, v123
	v_exp_f32_e32 v124, v124
	v_exp_f32_e32 v125, v125
	ds_read_b128 v[166:169], v204 offset:2048
	ds_read_b128 v[170:173], v204 offset:2560
	s_waitcnt lgkmcnt(12)
	v_mfma_f32_32x32x16_bf16 v[18:33], v[154:157], v[86:89], v[18:33]
	v_exp_f32_e32 v126, v126
	v_exp_f32_e32 v127, v127
	v_exp_f32_e32 v128, v128
	v_exp_f32_e32 v129, v129
	ds_read_b128 v[174:177], v204 offset:4096
	ds_read_b128 v[178:181], v204 offset:4608
	s_waitcnt lgkmcnt(12)
	v_mfma_f32_32x32x16_bf16 v[2:17], v[146:149], v[90:93], v[2:17]
	v_exp_f32_e32 v98, v98
	v_exp_f32_e32 v99, v99
	v_exp_f32_e32 v100, v100
	v_exp_f32_e32 v101, v101
	ds_read_b128 v[182:185], v204 offset:6144
	ds_read_b128 v[52:55], v204 offset:6656
	s_waitcnt lgkmcnt(12)
	v_mfma_f32_32x32x16_bf16 v[18:33], v[146:149], v[64:67], v[18:33]
	v_exp_f32_e32 v102, v102
	v_exp_f32_e32 v103, v103
	v_exp_f32_e32 v104, v104
	v_exp_f32_e32 v105, v105
	s_waitcnt lgkmcnt(10)
	v_mfma_f32_32x32x16_bf16 v[2:17], v[142:145], v[68:71], v[2:17]
	v_exp_f32_e32 v106, v106
	v_exp_f32_e32 v107, v107
	v_exp_f32_e32 v108, v108
	v_exp_f32_e32 v109, v109
	s_waitcnt lgkmcnt(8)
	v_mfma_f32_32x32x16_bf16 v[18:33], v[142:145], v[72:75], v[18:33]
	v_exp_f32_e32 v110, v110
	v_exp_f32_e32 v111, v111
	v_exp_f32_e32 v112, v112
	v_exp_f32_e32 v113, v113
	s_add_i32 s6, s76, 0x2000
	s_cmpk_lg_i32 s76, 0x4000
	s_cselect_b32 s31, s6, 0
	s_waitcnt vmcnt(2) lgkmcnt(0)
	s_barrier
	v_mfma_f32_32x32x16_bf16 v[82:97], v[60:63], v[150:153], v[34:49]
	ds_read_b64_tr_b16 v[186:187], v200 offset:24576
	ds_read_b64_tr_b16 v[188:189], v200 offset:25088
	v_add_f32_e32 v50, v114, v50
	v_add_f32_e32 v194, v115, v194
	v_add_f32_e32 v195, v116, v195
	v_add_f32_e32 v196, v117, v196
	v_add_f32_e32 v50, v118, v50
	v_add_f32_e32 v194, v119, v194
	v_cvt_pk_bf16_f32 v158, v114, v115
	v_cvt_pk_bf16_f32 v159, v116, v117
	v_mfma_f32_32x32x16_bf16 v[66:81], v[162:165], v[150:153], v[34:49]
	ds_read_b64_tr_b16 v[60:61], v200 offset:28672
	ds_read_b64_tr_b16 v[62:63], v200 offset:29184
	v_add_f32_e32 v195, v120, v195
	v_add_f32_e32 v196, v121, v196
	v_add_f32_e32 v50, v122, v50
	v_add_f32_e32 v194, v123, v194
	v_cvt_pk_bf16_f32 v160, v118, v119
	v_cvt_pk_bf16_f32 v161, v120, v121
	v_mfma_f32_32x32x16_bf16 v[82:97], v[166:169], v[138:141], v[82:97]
	ds_read_b64_tr_b16 v[114:115], v200 offset:25600
	ds_read_b64_tr_b16 v[116:117], v200 offset:26112
	v_add_f32_e32 v195, v124, v195
	v_add_f32_e32 v196, v125, v196
	v_add_f32_e32 v50, v126, v50
	v_add_f32_e32 v194, v127, v194
	v_cvt_pk_bf16_f32 v154, v122, v123
	v_cvt_pk_bf16_f32 v155, v124, v125
	v_mfma_f32_32x32x16_bf16 v[66:81], v[170:173], v[138:141], v[66:81]
	ds_read_b64_tr_b16 v[118:119], v200 offset:29696
	ds_read_b64_tr_b16 v[120:121], v200 offset:30208
	v_add_f32_e32 v195, v128, v195
	v_add_f32_e32 v196, v129, v196
	v_add_f32_e32 v50, v98, v50
	v_add_f32_e32 v194, v99, v194
	v_cvt_pk_bf16_f32 v156, v126, v127
	v_cvt_pk_bf16_f32 v157, v128, v129
	v_mfma_f32_32x32x16_bf16 v[82:97], v[174:177], v[134:137], v[82:97]
	ds_read_b64_tr_b16 v[122:123], v200 offset:26624
	ds_read_b64_tr_b16 v[124:125], v200 offset:27136
	v_add_f32_e32 v195, v100, v195
	v_add_f32_e32 v196, v101, v196
	v_add_f32_e32 v50, v102, v50
	v_add_f32_e32 v194, v103, v194
	v_cvt_pk_bf16_f32 v146, v98, v99
	v_cvt_pk_bf16_f32 v147, v100, v101
	v_mfma_f32_32x32x16_bf16 v[66:81], v[178:181], v[134:137], v[66:81]
	ds_read_b64_tr_b16 v[98:99], v200 offset:30720
	ds_read_b64_tr_b16 v[100:101], v200 offset:31232
	v_add_f32_e32 v195, v104, v195
	v_add_f32_e32 v196, v105, v196
	v_add_f32_e32 v50, v106, v50
	v_add_f32_e32 v194, v107, v194
	v_cvt_pk_bf16_f32 v148, v102, v103
	v_cvt_pk_bf16_f32 v149, v104, v105
	v_mfma_f32_32x32x16_bf16 v[82:97], v[182:185], v[130:133], v[82:97]
	ds_read_b64_tr_b16 v[102:103], v200 offset:27648
	ds_read_b64_tr_b16 v[104:105], v200 offset:28160
	v_add_f32_e32 v195, v108, v195
	v_add_f32_e32 v196, v109, v196
	v_add_f32_e32 v50, v110, v50
	v_add_f32_e32 v194, v111, v194
	v_cvt_pk_bf16_f32 v142, v106, v107
	v_cvt_pk_bf16_f32 v143, v108, v109
	v_mfma_f32_32x32x16_bf16 v[66:81], v[52:55], v[130:133], v[66:81]
	ds_read_b64_tr_b16 v[106:107], v200 offset:31744
	ds_read_b64_tr_b16 v[108:109], v200 offset:32256
	v_add_f32_e32 v195, v112, v195
	v_add_f32_e32 v196, v113, v196
	v_cvt_pk_bf16_f32 v144, v110, v111
	v_cvt_pk_bf16_f32 v145, v112, v113
	s_add_i32 m0, s76, s70
	s_add_i32 s6, s31, s71
	global_load_lds_dwordx4 v197, s[98:99]
	s_mov_b32 m0, s6
	s_nop 0
	global_load_lds_dwordx4 v205, s[98:99]
	s_add_u32 s98, s98, 0x2000
	s_addc_u32 s99, s99, 0
	s_waitcnt lgkmcnt(14)
	v_mfma_f32_32x32x16_bf16 v[2:17], v[158:161], v[186:189], v[2:17]
	v_exp_f32_e32 v82, v82
	v_exp_f32_e32 v83, v83
	v_exp_f32_e32 v84, v84
	v_exp_f32_e32 v85, v85
	s_waitcnt lgkmcnt(12)
	v_mfma_f32_32x32x16_bf16 v[18:33], v[158:161], v[60:63], v[18:33]
	v_exp_f32_e32 v86, v86
	v_exp_f32_e32 v87, v87
	v_exp_f32_e32 v88, v88
	v_exp_f32_e32 v89, v89
	ds_read_b128 v[190:193], v202
	ds_read_b128 v[186:189], v202 offset:512
	s_waitcnt lgkmcnt(12)
	v_mfma_f32_32x32x16_bf16 v[2:17], v[154:157], v[114:117], v[2:17]
	v_exp_f32_e32 v90, v90
	v_exp_f32_e32 v91, v91
	v_exp_f32_e32 v92, v92
	v_exp_f32_e32 v93, v93
	ds_read_b128 v[182:185], v202 offset:2048
	ds_read_b128 v[178:181], v202 offset:2560
	s_waitcnt lgkmcnt(12)
	v_mfma_f32_32x32x16_bf16 v[18:33], v[154:157], v[118:121], v[18:33]
	v_exp_f32_e32 v94, v94
	v_exp_f32_e32 v95, v95
	v_exp_f32_e32 v96, v96
	v_exp_f32_e32 v97, v97
	ds_read_b128 v[174:177], v202 offset:4096
	ds_read_b128 v[170:173], v202 offset:4608
	s_waitcnt lgkmcnt(12)
	v_mfma_f32_32x32x16_bf16 v[2:17], v[146:149], v[122:125], v[2:17]
	v_exp_f32_e32 v66, v66
	v_exp_f32_e32 v67, v67
	v_exp_f32_e32 v68, v68
	v_exp_f32_e32 v69, v69
	ds_read_b128 v[166:169], v202 offset:6144
	ds_read_b128 v[162:165], v202 offset:6656
	s_waitcnt lgkmcnt(12)
	v_mfma_f32_32x32x16_bf16 v[18:33], v[146:149], v[98:101], v[18:33]
	v_exp_f32_e32 v70, v70
	v_exp_f32_e32 v71, v71
	v_exp_f32_e32 v72, v72
	v_exp_f32_e32 v73, v73
	s_waitcnt lgkmcnt(10)
	v_mfma_f32_32x32x16_bf16 v[2:17], v[142:145], v[102:105], v[2:17]
	v_exp_f32_e32 v74, v74
	v_exp_f32_e32 v75, v75
	v_exp_f32_e32 v76, v76
	v_exp_f32_e32 v77, v77
	s_waitcnt lgkmcnt(8)
	v_mfma_f32_32x32x16_bf16 v[18:33], v[142:145], v[106:109], v[18:33]
	v_exp_f32_e32 v78, v78
	v_exp_f32_e32 v79, v79
	v_exp_f32_e32 v80, v80
	v_exp_f32_e32 v81, v81
	s_add_i32 s6, s31, 0x2000
	s_cmpk_lg_i32 s31, 0x4000
	s_mov_b32 s24, s76
	s_cselect_b32 s76, s6, 0
	s_add_i32 s26, s26, 2
	s_cmp_gt_i32 s26, s91
	s_cbranch_scc1 .Lattn_exit
	s_waitcnt vmcnt(2) lgkmcnt(0)
	s_barrier
.Lattn_cpB:
	v_mfma_f32_32x32x16_bf16 v[114:129], v[190:193], v[150:153], v[34:49]
	ds_read_b64_tr_b16 v[52:53], v201 offset:24576
	ds_read_b64_tr_b16 v[54:55], v201 offset:25088
	v_add_f32_e32 v50, v82, v50
	v_add_f32_e32 v194, v83, v194
	v_add_f32_e32 v195, v84, v195
	v_add_f32_e32 v196, v85, v196
	v_add_f32_e32 v50, v86, v50
	v_add_f32_e32 v194, v87, v194
	v_cvt_pk_bf16_f32 v158, v82, v83
	v_cvt_pk_bf16_f32 v159, v84, v85
	v_mfma_f32_32x32x16_bf16 v[98:113], v[186:189], v[150:153], v[34:49]
	ds_read_b64_tr_b16 v[60:61], v201 offset:28672
	ds_read_b64_tr_b16 v[62:63], v201 offset:29184
	v_add_f32_e32 v195, v88, v195
	v_add_f32_e32 v196, v89, v196
	v_add_f32_e32 v50, v90, v50
	v_add_f32_e32 v194, v91, v194
	v_cvt_pk_bf16_f32 v160, v86, v87
	v_cvt_pk_bf16_f32 v161, v88, v89
	v_mfma_f32_32x32x16_bf16 v[114:129], v[182:185], v[138:141], v[114:129]
	ds_read_b64_tr_b16 v[82:83], v201 offset:25600
	ds_read_b64_tr_b16 v[84:85], v201 offset:26112
	v_add_f32_e32 v195, v92, v195
	v_add_f32_e32 v196, v93, v196
	v_add_f32_e32 v50, v94, v50
	v_add_f32_e32 v194, v95, v194
	v_cvt_pk_bf16_f32 v154, v90, v91
	v_cvt_pk_bf16_f32 v155, v92, v93
	v_mfma_f32_32x32x16_bf16 v[98:113], v[178:181], v[138:141], v[98:113]
	ds_read_b64_tr_b16 v[86:87], v201 offset:29696
	ds_read_b64_tr_b16 v[88:89], v201 offset:30208
	v_add_f32_e32 v195, v96, v195
	v_add_f32_e32 v196, v97, v196
	v_add_f32_e32 v50, v66, v50
	v_add_f32_e32 v194, v67, v194
	v_cvt_pk_bf16_f32 v156, v94, v95
	v_cvt_pk_bf16_f32 v157, v96, v97
	v_mfma_f32_32x32x16_bf16 v[114:129], v[174:177], v[134:137], v[114:129]
	ds_read_b64_tr_b16 v[90:91], v201 offset:26624
	ds_read_b64_tr_b16 v[92:93], v201 offset:27136
	v_add_f32_e32 v195, v68, v195
	v_add_f32_e32 v196, v69, v196
	v_add_f32_e32 v50, v70, v50
	v_add_f32_e32 v194, v71, v194
	v_cvt_pk_bf16_f32 v146, v66, v67
	v_cvt_pk_bf16_f32 v147, v68, v69
	v_mfma_f32_32x32x16_bf16 v[98:113], v[170:173], v[134:137], v[98:113]
	ds_read_b64_tr_b16 v[64:65], v201 offset:30720
	ds_read_b64_tr_b16 v[66:67], v201 offset:31232
	v_add_f32_e32 v195, v72, v195
	v_add_f32_e32 v196, v73, v196
	v_add_f32_e32 v50, v74, v50
	v_add_f32_e32 v194, v75, v194
	v_cvt_pk_bf16_f32 v148, v70, v71
	v_cvt_pk_bf16_f32 v149, v72, v73
	v_mfma_f32_32x32x16_bf16 v[114:129], v[166:169], v[130:133], v[114:129]
	ds_read_b64_tr_b16 v[68:69], v201 offset:27648
	ds_read_b64_tr_b16 v[70:71], v201 offset:28160
	v_add_f32_e32 v195, v76, v195
	v_add_f32_e32 v196, v77, v196
	v_add_f32_e32 v50, v78, v50
	v_add_f32_e32 v194, v79, v194
	v_cvt_pk_bf16_f32 v142, v74, v75
	v_cvt_pk_bf16_f32 v143, v76, v77
	v_mfma_f32_32x32x16_bf16 v[98:113], v[162:165], v[130:133], v[98:113]
	ds_read_b64_tr_b16 v[72:73], v201 offset:31744
	ds_read_b64_tr_b16 v[74:75], v201 offset:32256
	v_add_f32_e32 v195, v80, v195
	v_add_f32_e32 v196, v81, v196
	v_cvt_pk_bf16_f32 v144, v78, v79
	v_cvt_pk_bf16_f32 v145, v80, v81
	s_add_i32 m0, s31, s70
	s_add_i32 s6, s76, s71
	global_load_lds_dwordx4 v197, s[98:99]
	s_mov_b32 m0, s6
	s_nop 0
	global_load_lds_dwordx4 v205, s[98:99]
	s_add_u32 s98, s98, 0x2000
	s_addc_u32 s99, s99, 0
	s_waitcnt lgkmcnt(14)
	v_mfma_f32_32x32x16_bf16 v[2:17], v[158:161], v[52:55], v[2:17]
	v_exp_f32_e32 v114, v114
	v_exp_f32_e32 v115, v115
	v_exp_f32_e32 v116, v116
	v_exp_f32_e32 v117, v117
	s_waitcnt lgkmcnt(12)
	v_mfma_f32_32x32x16_bf16 v[18:33], v[158:161], v[60:63], v[18:33]
	v_exp_f32_e32 v118, v118
	v_exp_f32_e32 v119, v119
	v_exp_f32_e32 v120, v120
	v_exp_f32_e32 v121, v121
	ds_read_b128 v[60:63], v203
	ds_read_b128 v[162:165], v203 offset:512
	s_waitcnt lgkmcnt(12)
	v_mfma_f32_32x32x16_bf16 v[2:17], v[154:157], v[82:85], v[2:17]
	v_exp_f32_e32 v122, v122
	v_exp_f32_e32 v123, v123
	v_exp_f32_e32 v124, v124
	v_exp_f32_e32 v125, v125
	ds_read_b128 v[166:169], v203 offset:2048
	ds_read_b128 v[170:173], v203 offset:2560
	s_waitcnt lgkmcnt(12)
	v_mfma_f32_32x32x16_bf16 v[18:33], v[154:157], v[86:89], v[18:33]
	v_exp_f32_e32 v126, v126
	v_exp_f32_e32 v127, v127
	v_exp_f32_e32 v128, v128
	v_exp_f32_e32 v129, v129
	ds_read_b128 v[174:177], v203 offset:4096
	ds_read_b128 v[178:181], v203 offset:4608
	s_waitcnt lgkmcnt(12)
	v_mfma_f32_32x32x16_bf16 v[2:17], v[146:149], v[90:93], v[2:17]
	v_exp_f32_e32 v98, v98
	v_exp_f32_e32 v99, v99
	v_exp_f32_e32 v100, v100
	v_exp_f32_e32 v101, v101
	ds_read_b128 v[182:185], v203 offset:6144
	ds_read_b128 v[52:55], v203 offset:6656
	s_waitcnt lgkmcnt(12)
	v_mfma_f32_32x32x16_bf16 v[18:33], v[146:149], v[64:67], v[18:33]
	v_exp_f32_e32 v102, v102
	v_exp_f32_e32 v103, v103
	v_exp_f32_e32 v104, v104
	v_exp_f32_e32 v105, v105
	s_waitcnt lgkmcnt(10)
	v_mfma_f32_32x32x16_bf16 v[2:17], v[142:145], v[68:71], v[2:17]
	v_exp_f32_e32 v106, v106
	v_exp_f32_e32 v107, v107
	v_exp_f32_e32 v108, v108
	v_exp_f32_e32 v109, v109
	s_waitcnt lgkmcnt(8)
	v_mfma_f32_32x32x16_bf16 v[18:33], v[142:145], v[72:75], v[18:33]
	v_exp_f32_e32 v110, v110
	v_exp_f32_e32 v111, v111
	v_exp_f32_e32 v112, v112
	v_exp_f32_e32 v113, v113
	s_add_i32 s6, s76, 0x2000
	s_cmpk_lg_i32 s76, 0x4000
	s_cselect_b32 s31, s6, 0
	s_waitcnt vmcnt(2) lgkmcnt(0)
	s_barrier
	v_mfma_f32_32x32x16_bf16 v[82:97], v[60:63], v[150:153], v[34:49]
	ds_read_b64_tr_b16 v[186:187], v199 offset:24576
	ds_read_b64_tr_b16 v[188:189], v199 offset:25088
	v_add_f32_e32 v50, v114, v50
	v_add_f32_e32 v194, v115, v194
	v_add_f32_e32 v195, v116, v195
	v_add_f32_e32 v196, v117, v196
	v_add_f32_e32 v50, v118, v50
	v_add_f32_e32 v194, v119, v194
	v_cvt_pk_bf16_f32 v158, v114, v115
	v_cvt_pk_bf16_f32 v159, v116, v117
	v_mfma_f32_32x32x16_bf16 v[66:81], v[162:165], v[150:153], v[34:49]
	ds_read_b64_tr_b16 v[60:61], v199 offset:28672
	ds_read_b64_tr_b16 v[62:63], v199 offset:29184
	v_add_f32_e32 v195, v120, v195
	v_add_f32_e32 v196, v121, v196
	v_add_f32_e32 v50, v122, v50
	v_add_f32_e32 v194, v123, v194
	v_cvt_pk_bf16_f32 v160, v118, v119
	v_cvt_pk_bf16_f32 v161, v120, v121
	v_mfma_f32_32x32x16_bf16 v[82:97], v[166:169], v[138:141], v[82:97]
	ds_read_b64_tr_b16 v[114:115], v199 offset:25600
	ds_read_b64_tr_b16 v[116:117], v199 offset:26112
	v_add_f32_e32 v195, v124, v195
	v_add_f32_e32 v196, v125, v196
	v_add_f32_e32 v50, v126, v50
	v_add_f32_e32 v194, v127, v194
	v_cvt_pk_bf16_f32 v154, v122, v123
	v_cvt_pk_bf16_f32 v155, v124, v125
	v_mfma_f32_32x32x16_bf16 v[66:81], v[170:173], v[138:141], v[66:81]
	ds_read_b64_tr_b16 v[118:119], v199 offset:29696
	ds_read_b64_tr_b16 v[120:121], v199 offset:30208
	v_add_f32_e32 v195, v128, v195
	v_add_f32_e32 v196, v129, v196
	v_add_f32_e32 v50, v98, v50
	v_add_f32_e32 v194, v99, v194
	v_cvt_pk_bf16_f32 v156, v126, v127
	v_cvt_pk_bf16_f32 v157, v128, v129
	v_mfma_f32_32x32x16_bf16 v[82:97], v[174:177], v[134:137], v[82:97]
	ds_read_b64_tr_b16 v[122:123], v199 offset:26624
	ds_read_b64_tr_b16 v[124:125], v199 offset:27136
	v_add_f32_e32 v195, v100, v195
	v_add_f32_e32 v196, v101, v196
	v_add_f32_e32 v50, v102, v50
	v_add_f32_e32 v194, v103, v194
	v_cvt_pk_bf16_f32 v146, v98, v99
	v_cvt_pk_bf16_f32 v147, v100, v101
	v_mfma_f32_32x32x16_bf16 v[66:81], v[178:181], v[134:137], v[66:81]
	ds_read_b64_tr_b16 v[98:99], v199 offset:30720
	ds_read_b64_tr_b16 v[100:101], v199 offset:31232
	v_add_f32_e32 v195, v104, v195
	v_add_f32_e32 v196, v105, v196
	v_add_f32_e32 v50, v106, v50
	v_add_f32_e32 v194, v107, v194
	v_cvt_pk_bf16_f32 v148, v102, v103
	v_cvt_pk_bf16_f32 v149, v104, v105
	v_mfma_f32_32x32x16_bf16 v[82:97], v[182:185], v[130:133], v[82:97]
	ds_read_b64_tr_b16 v[102:103], v199 offset:27648
	ds_read_b64_tr_b16 v[104:105], v199 offset:28160
	v_add_f32_e32 v195, v108, v195
	v_add_f32_e32 v196, v109, v196
	v_add_f32_e32 v50, v110, v50
	v_add_f32_e32 v194, v111, v194
	v_cvt_pk_bf16_f32 v142, v106, v107
	v_cvt_pk_bf16_f32 v143, v108, v109
	v_mfma_f32_32x32x16_bf16 v[66:81], v[52:55], v[130:133], v[66:81]
	ds_read_b64_tr_b16 v[106:107], v199 offset:31744
	ds_read_b64_tr_b16 v[108:109], v199 offset:32256
	v_add_f32_e32 v195, v112, v195
	v_add_f32_e32 v196, v113, v196
	v_cvt_pk_bf16_f32 v144, v110, v111
	v_cvt_pk_bf16_f32 v145, v112, v113
	s_add_i32 m0, s76, s70
	s_add_i32 s6, s31, s71
	global_load_lds_dwordx4 v197, s[98:99]
	s_mov_b32 m0, s6
	s_nop 0
	global_load_lds_dwordx4 v205, s[98:99]
	s_add_u32 s98, s98, 0x2000
	s_addc_u32 s99, s99, 0
	s_waitcnt lgkmcnt(14)
	v_mfma_f32_32x32x16_bf16 v[2:17], v[158:161], v[186:189], v[2:17]
	v_exp_f32_e32 v82, v82
	v_exp_f32_e32 v83, v83
	v_exp_f32_e32 v84, v84
	v_exp_f32_e32 v85, v85
	s_waitcnt lgkmcnt(12)
	v_mfma_f32_32x32x16_bf16 v[18:33], v[158:161], v[60:63], v[18:33]
	v_exp_f32_e32 v86, v86
	v_exp_f32_e32 v87, v87
	v_exp_f32_e32 v88, v88
	v_exp_f32_e32 v89, v89
	ds_read_b128 v[190:193], v204
	ds_read_b128 v[186:189], v204 offset:512
	s_waitcnt lgkmcnt(12)
	v_mfma_f32_32x32x16_bf16 v[2:17], v[154:157], v[114:117], v[2:17]
	v_exp_f32_e32 v90, v90
	v_exp_f32_e32 v91, v91
	v_exp_f32_e32 v92, v92
	v_exp_f32_e32 v93, v93
	ds_read_b128 v[182:185], v204 offset:2048
	ds_read_b128 v[178:181], v204 offset:2560
	s_waitcnt lgkmcnt(12)
	v_mfma_f32_32x32x16_bf16 v[18:33], v[154:157], v[118:121], v[18:33]
	v_exp_f32_e32 v94, v94
	v_exp_f32_e32 v95, v95
	v_exp_f32_e32 v96, v96
	v_exp_f32_e32 v97, v97
	ds_read_b128 v[174:177], v204 offset:4096
	ds_read_b128 v[170:173], v204 offset:4608
	s_waitcnt lgkmcnt(12)
	v_mfma_f32_32x32x16_bf16 v[2:17], v[146:149], v[122:125], v[2:17]
	v_exp_f32_e32 v66, v66
	v_exp_f32_e32 v67, v67
	v_exp_f32_e32 v68, v68
	v_exp_f32_e32 v69, v69
	ds_read_b128 v[166:169], v204 offset:6144
	ds_read_b128 v[162:165], v204 offset:6656
	s_waitcnt lgkmcnt(12)
	v_mfma_f32_32x32x16_bf16 v[18:33], v[146:149], v[98:101], v[18:33]
	v_exp_f32_e32 v70, v70
	v_exp_f32_e32 v71, v71
	v_exp_f32_e32 v72, v72
	v_exp_f32_e32 v73, v73
	s_waitcnt lgkmcnt(10)
	v_mfma_f32_32x32x16_bf16 v[2:17], v[142:145], v[102:105], v[2:17]
	v_exp_f32_e32 v74, v74
	v_exp_f32_e32 v75, v75
	v_exp_f32_e32 v76, v76
	v_exp_f32_e32 v77, v77
	s_waitcnt lgkmcnt(8)
	v_mfma_f32_32x32x16_bf16 v[18:33], v[142:145], v[106:109], v[18:33]
	v_exp_f32_e32 v78, v78
	v_exp_f32_e32 v79, v79
	v_exp_f32_e32 v80, v80
	v_exp_f32_e32 v81, v81
	s_add_i32 s6, s31, 0x2000
	s_cmpk_lg_i32 s31, 0x4000
	s_mov_b32 s24, s76
	s_cselect_b32 s76, s6, 0
	s_add_i32 s26, s26, 2
	s_cmp_gt_i32 s26, s91
	s_cbranch_scc1 .Lattn_exit
	s_waitcnt vmcnt(2) lgkmcnt(0)
	s_barrier
.Lattn_cpC:
	v_mfma_f32_32x32x16_bf16 v[114:129], v[190:193], v[150:153], v[34:49]
	ds_read_b64_tr_b16 v[52:53], v200 offset:24576
	ds_read_b64_tr_b16 v[54:55], v200 offset:25088
	v_add_f32_e32 v50, v82, v50
	v_add_f32_e32 v194, v83, v194
	v_add_f32_e32 v195, v84, v195
	v_add_f32_e32 v196, v85, v196
	v_add_f32_e32 v50, v86, v50
	v_add_f32_e32 v194, v87, v194
	v_cvt_pk_bf16_f32 v158, v82, v83
	v_cvt_pk_bf16_f32 v159, v84, v85
	v_mfma_f32_32x32x16_bf16 v[98:113], v[186:189], v[150:153], v[34:49]
	ds_read_b64_tr_b16 v[60:61], v200 offset:28672
	ds_read_b64_tr_b16 v[62:63], v200 offset:29184
	v_add_f32_e32 v195, v88, v195
	v_add_f32_e32 v196, v89, v196
	v_add_f32_e32 v50, v90, v50
	v_add_f32_e32 v194, v91, v194
	v_cvt_pk_bf16_f32 v160, v86, v87
	v_cvt_pk_bf16_f32 v161, v88, v89
	v_mfma_f32_32x32x16_bf16 v[114:129], v[182:185], v[138:141], v[114:129]
	ds_read_b64_tr_b16 v[82:83], v200 offset:25600
	ds_read_b64_tr_b16 v[84:85], v200 offset:26112
	v_add_f32_e32 v195, v92, v195
	v_add_f32_e32 v196, v93, v196
	v_add_f32_e32 v50, v94, v50
	v_add_f32_e32 v194, v95, v194
	v_cvt_pk_bf16_f32 v154, v90, v91
	v_cvt_pk_bf16_f32 v155, v92, v93
	v_mfma_f32_32x32x16_bf16 v[98:113], v[178:181], v[138:141], v[98:113]
	ds_read_b64_tr_b16 v[86:87], v200 offset:29696
	ds_read_b64_tr_b16 v[88:89], v200 offset:30208
	v_add_f32_e32 v195, v96, v195
	v_add_f32_e32 v196, v97, v196
	v_add_f32_e32 v50, v66, v50
	v_add_f32_e32 v194, v67, v194
	v_cvt_pk_bf16_f32 v156, v94, v95
	v_cvt_pk_bf16_f32 v157, v96, v97
	v_mfma_f32_32x32x16_bf16 v[114:129], v[174:177], v[134:137], v[114:129]
	ds_read_b64_tr_b16 v[90:91], v200 offset:26624
	ds_read_b64_tr_b16 v[92:93], v200 offset:27136
	v_add_f32_e32 v195, v68, v195
	v_add_f32_e32 v196, v69, v196
	v_add_f32_e32 v50, v70, v50
	v_add_f32_e32 v194, v71, v194
	v_cvt_pk_bf16_f32 v146, v66, v67
	v_cvt_pk_bf16_f32 v147, v68, v69
	v_mfma_f32_32x32x16_bf16 v[98:113], v[170:173], v[134:137], v[98:113]
	ds_read_b64_tr_b16 v[64:65], v200 offset:30720
	ds_read_b64_tr_b16 v[66:67], v200 offset:31232
	v_add_f32_e32 v195, v72, v195
	v_add_f32_e32 v196, v73, v196
	v_add_f32_e32 v50, v74, v50
	v_add_f32_e32 v194, v75, v194
	v_cvt_pk_bf16_f32 v148, v70, v71
	v_cvt_pk_bf16_f32 v149, v72, v73
	v_mfma_f32_32x32x16_bf16 v[114:129], v[166:169], v[130:133], v[114:129]
	ds_read_b64_tr_b16 v[68:69], v200 offset:27648
	ds_read_b64_tr_b16 v[70:71], v200 offset:28160
	v_add_f32_e32 v195, v76, v195
	v_add_f32_e32 v196, v77, v196
	v_add_f32_e32 v50, v78, v50
	v_add_f32_e32 v194, v79, v194
	v_cvt_pk_bf16_f32 v142, v74, v75
	v_cvt_pk_bf16_f32 v143, v76, v77
	v_mfma_f32_32x32x16_bf16 v[98:113], v[162:165], v[130:133], v[98:113]
	ds_read_b64_tr_b16 v[72:73], v200 offset:31744
	ds_read_b64_tr_b16 v[74:75], v200 offset:32256
	v_add_f32_e32 v195, v80, v195
	v_add_f32_e32 v196, v81, v196
	v_cvt_pk_bf16_f32 v144, v78, v79
	v_cvt_pk_bf16_f32 v145, v80, v81
	s_add_i32 m0, s31, s70
	s_add_i32 s6, s76, s71
	global_load_lds_dwordx4 v197, s[98:99]
	s_mov_b32 m0, s6
	s_nop 0
	global_load_lds_dwordx4 v205, s[98:99]
	s_add_u32 s98, s98, 0x2000
	s_addc_u32 s99, s99, 0
	s_waitcnt lgkmcnt(14)
	v_mfma_f32_32x32x16_bf16 v[2:17], v[158:161], v[52:55], v[2:17]
	v_exp_f32_e32 v114, v114
	v_exp_f32_e32 v115, v115
	v_exp_f32_e32 v116, v116
	v_exp_f32_e32 v117, v117
	s_waitcnt lgkmcnt(12)
	v_mfma_f32_32x32x16_bf16 v[18:33], v[158:161], v[60:63], v[18:33]
	v_exp_f32_e32 v118, v118
	v_exp_f32_e32 v119, v119
	v_exp_f32_e32 v120, v120
	v_exp_f32_e32 v121, v121
	ds_read_b128 v[60:63], v202
	ds_read_b128 v[162:165], v202 offset:512
	s_waitcnt lgkmcnt(12)
	v_mfma_f32_32x32x16_bf16 v[2:17], v[154:157], v[82:85], v[2:17]
	v_exp_f32_e32 v122, v122
	v_exp_f32_e32 v123, v123
	v_exp_f32_e32 v124, v124
	v_exp_f32_e32 v125, v125
	ds_read_b128 v[166:169], v202 offset:2048
	ds_read_b128 v[170:173], v202 offset:2560
	s_waitcnt lgkmcnt(12)
	v_mfma_f32_32x32x16_bf16 v[18:33], v[154:157], v[86:89], v[18:33]
	v_exp_f32_e32 v126, v126
	v_exp_f32_e32 v127, v127
	v_exp_f32_e32 v128, v128
	v_exp_f32_e32 v129, v129
	ds_read_b128 v[174:177], v202 offset:4096
	ds_read_b128 v[178:181], v202 offset:4608
	s_waitcnt lgkmcnt(12)
	v_mfma_f32_32x32x16_bf16 v[2:17], v[146:149], v[90:93], v[2:17]
	v_exp_f32_e32 v98, v98
	v_exp_f32_e32 v99, v99
	v_exp_f32_e32 v100, v100
	v_exp_f32_e32 v101, v101
	ds_read_b128 v[182:185], v202 offset:6144
	ds_read_b128 v[52:55], v202 offset:6656
	s_waitcnt lgkmcnt(12)
	v_mfma_f32_32x32x16_bf16 v[18:33], v[146:149], v[64:67], v[18:33]
	v_exp_f32_e32 v102, v102
	v_exp_f32_e32 v103, v103
	v_exp_f32_e32 v104, v104
	v_exp_f32_e32 v105, v105
	s_waitcnt lgkmcnt(10)
	v_mfma_f32_32x32x16_bf16 v[2:17], v[142:145], v[68:71], v[2:17]
	v_exp_f32_e32 v106, v106
	v_exp_f32_e32 v107, v107
	v_exp_f32_e32 v108, v108
	v_exp_f32_e32 v109, v109
	s_waitcnt lgkmcnt(8)
	v_mfma_f32_32x32x16_bf16 v[18:33], v[142:145], v[72:75], v[18:33]
	v_exp_f32_e32 v110, v110
	v_exp_f32_e32 v111, v111
	v_exp_f32_e32 v112, v112
	v_exp_f32_e32 v113, v113
	s_add_i32 s6, s76, 0x2000
	s_cmpk_lg_i32 s76, 0x4000
	s_cselect_b32 s31, s6, 0
	s_waitcnt vmcnt(2) lgkmcnt(0)
	s_barrier
; #define WAIT_BAR(N) asm volatile("s_waitcnt vmcnt(" #N ") lgkmcnt(0)\n\ts_barrier":::"memory")
;   #define RESC() do{ if(resc){ asm volatile("s_waitcnt lgkmcnt(0)":::"memory"); \
;       _Pragma("unroll") for(int d_=0;d_<2;++d_) _Pragma("unroll") for(int r=0;r<16;++r)o[d_][r]*=wsf[crow(r,hi)]; } }while(0)
;   #define ROT() do{sl_prev=sl_cur;sl_cur=sl_next;sl_next=(sl_next==(NSLOT-1)*SLOTB)?0:sl_next+SLOTB;}while(0)
; template<int THRL> __device__ __forceinline__ void attn_unit(const bf16*Qu,const bf16*__restrict__ Kh,const bf16*__restrict__ Vh,bf16*Ou,const int NT,const float shift,char*shm){
;     ...
;   for(;t+5<NT;t+=2){
;     STEP(pB0,pB1,pA0,pA1,t,true,true,true);     WAIT_BAR(2); RESC(); ROT();
;     STEP(pA0,pA1,pB0,pB1,t+1,true,true,true);   WAIT_BAR(2); RESC(); ROT();
;   }
	v_mfma_f32_32x32x16_bf16 v[82:97], v[60:63], v[150:153], v[34:49]
	ds_read_b64_tr_b16 v[186:187], v201 offset:24576
	ds_read_b64_tr_b16 v[188:189], v201 offset:25088
	v_add_f32_e32 v50, v114, v50
	v_add_f32_e32 v194, v115, v194
	v_add_f32_e32 v195, v116, v195
	v_add_f32_e32 v196, v117, v196
	v_add_f32_e32 v50, v118, v50
	v_add_f32_e32 v194, v119, v194
	v_cvt_pk_bf16_f32 v158, v114, v115
	v_cvt_pk_bf16_f32 v159, v116, v117
	v_mfma_f32_32x32x16_bf16 v[66:81], v[162:165], v[150:153], v[34:49]
	ds_read_b64_tr_b16 v[60:61], v201 offset:28672
	ds_read_b64_tr_b16 v[62:63], v201 offset:29184
	v_add_f32_e32 v195, v120, v195
	v_add_f32_e32 v196, v121, v196
	v_add_f32_e32 v50, v122, v50
	v_add_f32_e32 v194, v123, v194
	v_cvt_pk_bf16_f32 v160, v118, v119
	v_cvt_pk_bf16_f32 v161, v120, v121
	v_mfma_f32_32x32x16_bf16 v[82:97], v[166:169], v[138:141], v[82:97]
	ds_read_b64_tr_b16 v[114:115], v201 offset:25600
	ds_read_b64_tr_b16 v[116:117], v201 offset:26112
	v_add_f32_e32 v195, v124, v195
	v_add_f32_e32 v196, v125, v196
	v_add_f32_e32 v50, v126, v50
	v_add_f32_e32 v194, v127, v194
	v_cvt_pk_bf16_f32 v154, v122, v123
	v_cvt_pk_bf16_f32 v155, v124, v125
	v_mfma_f32_32x32x16_bf16 v[66:81], v[170:173], v[138:141], v[66:81]
	ds_read_b64_tr_b16 v[118:119], v201 offset:29696
	ds_read_b64_tr_b16 v[120:121], v201 offset:30208
	v_add_f32_e32 v195, v128, v195
	v_add_f32_e32 v196, v129, v196
	v_add_f32_e32 v50, v98, v50
	v_add_f32_e32 v194, v99, v194
	v_cvt_pk_bf16_f32 v156, v126, v127
	v_cvt_pk_bf16_f32 v157, v128, v129
	v_mfma_f32_32x32x16_bf16 v[82:97], v[174:177], v[134:137], v[82:97]
	ds_read_b64_tr_b16 v[122:123], v201 offset:26624
	ds_read_b64_tr_b16 v[124:125], v201 offset:27136
	v_add_f32_e32 v195, v100, v195
	v_add_f32_e32 v196, v101, v196
	v_add_f32_e32 v50, v102, v50
	v_add_f32_e32 v194, v103, v194
	v_cvt_pk_bf16_f32 v146, v98, v99
	v_cvt_pk_bf16_f32 v147, v100, v101
	v_mfma_f32_32x32x16_bf16 v[66:81], v[178:181], v[134:137], v[66:81]
	ds_read_b64_tr_b16 v[98:99], v201 offset:30720
	ds_read_b64_tr_b16 v[100:101], v201 offset:31232
	v_add_f32_e32 v195, v104, v195
	v_add_f32_e32 v196, v105, v196
	v_add_f32_e32 v50, v106, v50
	v_add_f32_e32 v194, v107, v194
	v_cvt_pk_bf16_f32 v148, v102, v103
	v_cvt_pk_bf16_f32 v149, v104, v105
	v_mfma_f32_32x32x16_bf16 v[82:97], v[182:185], v[130:133], v[82:97]
	ds_read_b64_tr_b16 v[102:103], v201 offset:27648
	ds_read_b64_tr_b16 v[104:105], v201 offset:28160
	v_add_f32_e32 v195, v108, v195
	v_add_f32_e32 v196, v109, v196
	v_add_f32_e32 v50, v110, v50
	v_add_f32_e32 v194, v111, v194
	v_cvt_pk_bf16_f32 v142, v106, v107
	v_cvt_pk_bf16_f32 v143, v108, v109
	v_mfma_f32_32x32x16_bf16 v[66:81], v[52:55], v[130:133], v[66:81]
	ds_read_b64_tr_b16 v[106:107], v201 offset:31744
	ds_read_b64_tr_b16 v[108:109], v201 offset:32256
	v_add_f32_e32 v195, v112, v195
	v_add_f32_e32 v196, v113, v196
	v_cvt_pk_bf16_f32 v144, v110, v111
	v_cvt_pk_bf16_f32 v145, v112, v113
	s_add_i32 m0, s76, s70
	s_add_i32 s6, s31, s71
	global_load_lds_dwordx4 v197, s[98:99]
	s_mov_b32 m0, s6
	s_nop 0
	global_load_lds_dwordx4 v205, s[98:99]
	s_add_u32 s98, s98, 0x2000
	s_addc_u32 s99, s99, 0
	s_waitcnt lgkmcnt(14)
	v_mfma_f32_32x32x16_bf16 v[2:17], v[158:161], v[186:189], v[2:17]
	v_exp_f32_e32 v82, v82
	v_exp_f32_e32 v83, v83
	v_exp_f32_e32 v84, v84
	v_exp_f32_e32 v85, v85
	s_waitcnt lgkmcnt(12)
	v_mfma_f32_32x32x16_bf16 v[18:33], v[158:161], v[60:63], v[18:33]
	v_exp_f32_e32 v86, v86
	v_exp_f32_e32 v87, v87
	v_exp_f32_e32 v88, v88
	v_exp_f32_e32 v89, v89
	ds_read_b128 v[190:193], v203
	ds_read_b128 v[186:189], v203 offset:512
	s_waitcnt lgkmcnt(12)
	v_mfma_f32_32x32x16_bf16 v[2:17], v[154:157], v[114:117], v[2:17]
	v_exp_f32_e32 v90, v90
	v_exp_f32_e32 v91, v91
	v_exp_f32_e32 v92, v92
	v_exp_f32_e32 v93, v93
	ds_read_b128 v[182:185], v203 offset:2048
	ds_read_b128 v[178:181], v203 offset:2560
	s_waitcnt lgkmcnt(12)
	v_mfma_f32_32x32x16_bf16 v[18:33], v[154:157], v[118:121], v[18:33]
	v_exp_f32_e32 v94, v94
	v_exp_f32_e32 v95, v95
	v_exp_f32_e32 v96, v96
	v_exp_f32_e32 v97, v97
	ds_read_b128 v[174:177], v203 offset:4096
	ds_read_b128 v[170:173], v203 offset:4608
	s_waitcnt lgkmcnt(12)
	v_mfma_f32_32x32x16_bf16 v[2:17], v[146:149], v[122:125], v[2:17]
	v_exp_f32_e32 v66, v66
	v_exp_f32_e32 v67, v67
	v_exp_f32_e32 v68, v68
	v_exp_f32_e32 v69, v69
	ds_read_b128 v[166:169], v203 offset:6144
	ds_read_b128 v[162:165], v203 offset:6656
	s_waitcnt lgkmcnt(12)
	v_mfma_f32_32x32x16_bf16 v[18:33], v[146:149], v[98:101], v[18:33]
	v_exp_f32_e32 v70, v70
	v_exp_f32_e32 v71, v71
	v_exp_f32_e32 v72, v72
	v_exp_f32_e32 v73, v73
	s_waitcnt lgkmcnt(10)
	v_mfma_f32_32x32x16_bf16 v[2:17], v[142:145], v[102:105], v[2:17]
	v_exp_f32_e32 v74, v74
	v_exp_f32_e32 v75, v75
	v_exp_f32_e32 v76, v76
	v_exp_f32_e32 v77, v77
	s_waitcnt lgkmcnt(8)
	v_mfma_f32_32x32x16_bf16 v[18:33], v[142:145], v[106:109], v[18:33]
	v_exp_f32_e32 v78, v78
	v_exp_f32_e32 v79, v79
	v_exp_f32_e32 v80, v80
	v_exp_f32_e32 v81, v81
	s_add_i32 s6, s31, 0x2000
	s_cmpk_lg_i32 s31, 0x4000
	s_mov_b32 s24, s76
	s_cselect_b32 s76, s6, 0
	s_add_i32 s26, s26, 2
	s_cmp_gt_i32 s26, s91
	s_cbranch_scc0 .Lattn_rot
